# forgetting-attention loop without the s_setprio raise around role B's MFMA block (priority re-tuned after the store restructuring)
# baseline (speedup 1.0000x reference)
; __device__ __forceinline__ s16x4 vtr(ldsp p) { return __builtin_bit_cast(s16x4, __builtin_amdgcn_ds_read_tr16_b64_v4i16((LAS v4i16_t*)p)); }
; #define MASK_BLOCK() do { if (kt == 0 || kt >= diag0) { \
;             _Pragma("unroll") for (int r = 0; r < 16; ++r) { const int kpp = 64 * kt + crow(r, hi); \
;                 if (kpp < 48 || kpp > q_pp) s0[r] = -INFINITY; \
;                 if (kpp + 32 < 48 || kpp + 32 > q_pp) s1[r] = -INFINITY; } } } while (0)
; #define EXPSUM_BLOCK() do { psa = 0.f; psb = 0.f; \
;             _Pragma("unroll") for (int r = 0; r < 16; ++r) { s0[r] = __builtin_amdgcn_exp2f(s0[r]); s1[r] = __builtin_amdgcn_exp2f(s1[r]); psa += s0[r]; asm("" : "+v"(psa)); psb += s1[r]; asm("" : "+v"(psb)); } } while (0)
; template <bool DIFF>
; __device__ __forceinline__ void attn_unit(const AttnP& A, int b, int h, int qi, ldsp lds) {
;     ...
;             QK_BLOCK();
;             s16x4 vlo[8], vhi[8];
; #pragma unroll
;             for (int t = 0; t < 2; ++t)
; #pragma unroll
;                 for (int j = 0; j < 4; ++j) { vlo[t * 4 + j] = vtr(Vb + trb + (16 * j) * VP + t * 64); vhi[t * 4 + j] = vtr(Vb + trb + (16 * j + 8) * VP + t * 64); }
;             __builtin_amdgcn_sched_barrier(0);
;             MASK_BLOCK();
;             bool full = (kt == kt0);
;             float psa, psb;
;             if (!full) {
;                 EXPSUM_BLOCK();
;                 if (__any(psa + psb > 1.0e18f)) { full = true; QK_BLOCK();
.Lfb_s_top:
	s_bitcmp1_b32 s99, 0
	s_cselect_b32 s74, 0x5500, 0
	s_sub_i32 s75, 0x5500, s74
	v_exp_f32_e32 v106, v66
	v_exp_f32_e32 v124, v50
	v_exp_f32_e32 v107, v67
	v_exp_f32_e32 v125, v51
	v_add_f32_e32 v166, 0, v106
	v_add_f32_e32 v167, 0, v124
	v_exp_f32_e32 v108, v68
	v_exp_f32_e32 v126, v52
	v_add_f32_e32 v166, v107, v166
	v_add_f32_e32 v167, v125, v167
	v_exp_f32_e32 v109, v69
	v_exp_f32_e32 v127, v53
	v_add_f32_e32 v166, v108, v166
	v_add_f32_e32 v167, v126, v167
	v_exp_f32_e32 v110, v70
	v_exp_f32_e32 v128, v54
	v_add_f32_e32 v166, v109, v166
	v_add_f32_e32 v167, v127, v167
	v_exp_f32_e32 v111, v71
	v_exp_f32_e32 v129, v55
	v_add_f32_e32 v166, v110, v166
	v_add_f32_e32 v167, v128, v167
	v_exp_f32_e32 v112, v72
	v_exp_f32_e32 v130, v56
	v_add_f32_e32 v166, v111, v166
	v_add_f32_e32 v167, v129, v167
	v_exp_f32_e32 v113, v73
	v_exp_f32_e32 v131, v57
	v_add_f32_e32 v166, v112, v166
	v_add_f32_e32 v167, v130, v167
	v_exp_f32_e32 v116, v74
	v_exp_f32_e32 v132, v58
	v_add_f32_e32 v166, v113, v166
	v_add_f32_e32 v167, v131, v167
	v_exp_f32_e32 v117, v75
	v_exp_f32_e32 v133, v59
	v_add_f32_e32 v166, v116, v166
	v_add_f32_e32 v167, v132, v167
	v_exp_f32_e32 v118, v76
	v_exp_f32_e32 v134, v60
	v_add_f32_e32 v166, v117, v166
	v_add_f32_e32 v167, v133, v167
	v_exp_f32_e32 v119, v77
	v_exp_f32_e32 v135, v61
	v_add_f32_e32 v166, v118, v166
	v_add_f32_e32 v167, v134, v167
	v_exp_f32_e32 v120, v78
	v_exp_f32_e32 v136, v62
	v_add_f32_e32 v166, v119, v166
	v_add_f32_e32 v167, v135, v167
	v_exp_f32_e32 v121, v79
	v_exp_f32_e32 v137, v63
	v_add_f32_e32 v166, v120, v166
	v_add_f32_e32 v167, v136, v167
	v_exp_f32_e32 v122, v80
	v_exp_f32_e32 v138, v64
	v_add_f32_e32 v166, v121, v166
	v_add_f32_e32 v167, v137, v167
	v_exp_f32_e32 v123, v81
	v_exp_f32_e32 v139, v65
	v_add_f32_e32 v166, v122, v166
	v_add_f32_e32 v167, v138, v167
	s_nop 0
	v_add_f32_e32 v166, v123, v166
	v_add_f32_e32 v167, v139, v167
	v_add_f32_e32 v141, v166, v167
	v_cmp_lt_f32_e32 vcc, s85, v141
	s_cbranch_vccnz .Lfb_s_slow
; __device__ __forceinline__ unsigned cvtpk(float lo, float hi) { f32x2 v = {lo, hi}; bf16x2_t b = __builtin_convertvector(v, bf16x2_t); return __builtin_bit_cast(unsigned, b); }
; template <bool DIFF>
; __device__ __forceinline__ void attn_unit(const AttnP& A, int b, int h, int qi, ldsp lds) {
;     ...
;             bf16x8 pw[4];
; #pragma unroll
;             for (int j = 0; j < 4; ++j) {
;                 u32x4 pk;
;                 if (j < 2) { const int rb = 8 * (j & 1); pk.x = cvtpk(s0[rb], s0[rb + 1]); pk.y = cvtpk(s0[rb + 2], s0[rb + 3]); pk.z = cvtpk(s0[rb + 4], s0[rb + 5]); pk.w = cvtpk(s0[rb + 6], s0[rb + 7]); }
;                 else { const int rb = 8 * (j & 1); pk.x = cvtpk(s1[rb], s1[rb + 1]); pk.y = cvtpk(s1[rb + 2], s1[rb + 3]); pk.z = cvtpk(s1[rb + 4], s1[rb + 5]); pk.w = cvtpk(s1[rb + 6], s1[rb + 7]); }
;                 pw[j] = __builtin_bit_cast(bf16x8, pk);
;             }
;             __builtin_amdgcn_sched_barrier(0);
;             __builtin_amdgcn_s_setprio(1);
; #pragma unroll
;             for (int t = 0; t < 2; ++t)
; #pragma unroll
;                 for (int j = 0; j < 4; ++j) {
;                     const bf16x8 vf = (bf16x8){vlo[t * 4 + j][0], vlo[t * 4 + j][1], vlo[t * 4 + j][2], vlo[t * 4 + j][3], vhi[t * 4 + j][0], vhi[t * 4 + j][1], vhi[t * 4 + j][2], vhi[t * 4 + j][3]};
;                     o[t] = __builtin_amdgcn_mfma_f32_32x32x16_bf16(vf, pw[j], o[t], 0, 0, 0);
;                 }
;             if (DIFF) {
; #pragma unroll
;                 for (int t = 2; t < NTD; ++t)
; #pragma unroll
;                     for (int j = 0; j < 4; ++j) { vlo[(t - 2) * 4 + j] = vtr(Vb + trb + (16 * j) * VP + t * 64); vhi[(t - 2) * 4 + j] = vtr(Vb + trb + (16 * j + 8) * VP + t * 64); }
;                 __builtin_amdgcn_sched_barrier(0);
; #pragma unroll
;                 for (int t = 2; t < NTD; ++t)
; #pragma unroll
;                     for (int j = 0; j < 4; ++j) {
;                         const int i = (t - 2) * 4 + j;
;                         const bf16x8 vf = (bf16x8){vlo[i][0], vlo[i][1], vlo[i][2], vlo[i][3], vhi[i][0], vhi[i][1], vhi[i][2], vhi[i][3]};
;                         o[t] = __builtin_amdgcn_mfma_f32_32x32x16_bf16(vf, pw[j], o[t], 0, 0, 0);
;                     }
;             }
;             __builtin_amdgcn_s_setprio(0);
;         }
;         if (kt + 1 < nt) STORE_TILE((kt + 1) & 1);
;         __syncthreads();
;     }
	v_add_u32_e32 v169, s74, v150
	v_add_u32_e32 v0, s74, v164
	v_add_u32_e32 v168, s75, v161
	ds_read_b64_tr_b16 v[58:59], v168 offset:9216
	ds_read_b64_tr_b16 v[60:61], v168 offset:10752
	ds_read_b64_tr_b16 v[62:63], v168 offset:9280
	ds_read_b64_tr_b16 v[64:65], v168 offset:10816
	ds_read_b64_tr_b16 v[74:75], v168 offset:12288
	ds_read_b64_tr_b16 v[76:77], v168 offset:13824
	ds_read_b64_tr_b16 v[78:79], v168 offset:12352
	ds_read_b64_tr_b16 v[80:81], v168 offset:13888
	ds_read_b64_tr_b16 v[244:245], v168 offset:15360
	ds_read_b64_tr_b16 v[246:247], v168 offset:16896
	v_cvt_pk_bf16_f32 v66, v106, v107
	v_cvt_pk_bf16_f32 v67, v108, v109
	v_cvt_pk_bf16_f32 v68, v110, v111
	v_cvt_pk_bf16_f32 v69, v112, v113
	v_cvt_pk_bf16_f32 v70, v116, v117
	v_cvt_pk_bf16_f32 v71, v118, v119
	v_cvt_pk_bf16_f32 v72, v120, v121
	v_cvt_pk_bf16_f32 v73, v122, v123
	v_cvt_pk_bf16_f32 v50, v124, v125
	v_cvt_pk_bf16_f32 v51, v126, v127
	v_cvt_pk_bf16_f32 v52, v128, v129
	v_cvt_pk_bf16_f32 v53, v130, v131
	v_cvt_pk_bf16_f32 v54, v132, v133
	v_cvt_pk_bf16_f32 v55, v134, v135
	v_cvt_pk_bf16_f32 v56, v136, v137
	v_cvt_pk_bf16_f32 v57, v138, v139
	v_add_f32_e32 v154, v141, v154
	ds_read_b64_tr_b16 v[106:107], v168 offset:15424
	ds_read_b64_tr_b16 v[108:109], v168 offset:16960
	ds_read_b64_tr_b16 v[110:111], v168 offset:18432
	ds_read_b64_tr_b16 v[112:113], v168 offset:19968
	ds_read_b64_tr_b16 v[116:117], v168 offset:18496
	ds_read_b64_tr_b16 v[118:119], v168 offset:20032
	v_mov_b32_e32 v248, s97
	ds_read_b32 v248, v248
	ds_read_b128 v[120:123], v169
	ds_read_b128 v[124:127], v169 offset:4608
	ds_read_b128 v[128:131], v169 offset:32
	ds_read_b128 v[132:135], v169 offset:4640
	ds_read_b128 v[136:139], v169 offset:64
	ds_read_b128 v[170:173], v169 offset:4672
	s_waitcnt lgkmcnt(15)
	v_mfma_f32_32x32x16_bf16 v[18:33], v[58:61], v[66:69], v[18:33]
	v_mfma_f32_32x32x16_bf16 v[2:17], v[62:65], v[66:69], v[2:17]
	v_mfma_f32_32x32x16_bf16 v[18:33], v[74:77], v[70:73], v[18:33]
	v_mfma_f32_32x32x16_bf16 v[2:17], v[78:81], v[70:73], v[2:17]
	s_waitcnt lgkmcnt(13)
	v_mfma_f32_32x32x16_bf16 v[18:33], v[244:247], v[50:53], v[18:33]
	ds_read_b128 v[244:247], v169 offset:96
	s_waitcnt lgkmcnt(12)
	v_mfma_f32_32x32x16_bf16 v[2:17], v[106:109], v[50:53], v[2:17]
	ds_read_b128 v[106:109], v169 offset:4704
	s_waitcnt lgkmcnt(11)
	v_mfma_f32_32x32x16_bf16 v[18:33], v[110:113], v[54:57], v[18:33]
	ds_read_b128 v[110:113], v0 offset:128
	s_waitcnt lgkmcnt(10)
	v_mfma_f32_32x32x16_bf16 v[2:17], v[116:119], v[54:57], v[2:17]
	ds_read_b128 v[116:119], v0 offset:4736
	s_waitcnt vmcnt(0)
	v_add_u32_e32 v115, s75, v156
	ds_write_b128 v115, v[98:101]
	s_and_saveexec_b64 s[0:1], s[44:45]
	v_xor_b32_e32 v0, 0x80000000, v155
	v_cvt_pk_bf16_f32 v0, v0, 0
	v_lshlrev_b32_e32 v249, 16, v0
	v_sub_f32_e64 v249, -v155, v249
	v_cvt_pk_bf16_f32 v162, v249, 0
	v_lshlrev_b32_e32 v162, 16, v162
	v_sub_f32_e32 v249, v249, v162
	v_cvt_pk_bf16_f32 v249, v249, 0
	v_and_or_b32 v112, v0, s83, v162
	v_and_or_b32 v113, v249, s83, 1.0
	v_mov_b32_e32 v115, v1
	v_add_u32_e32 v0, s75, v159
	ds_write_b128 v0, v[112:115] offset:128
	s_mov_b64 exec, s[0:1]
	v_add_u32_e32 v115, s74, v158
	ds_write_b128 v115, v[102:105] offset:9216
	global_load_dwordx4 v[102:105], v[250:251], off
	v_lshl_add_u64 v[250:251], v[250:251], 0, s[26:27]
	global_load_dwordx4 v[98:101], v[152:153], off
	v_lshl_add_u64 v[152:153], v[152:153], 0, s[26:27]
	s_and_saveexec_b64 s[0:1], s[44:45]
	global_load_dword v155, v[252:253], off
	s_mov_b64 exec, s[0:1]
	s_mov_b64 s[0:1], 0x800
	v_lshl_add_u64 v[252:253], v[252:253], 0, s[0:1]
	s_waitcnt lgkmcnt(12)
	v_mfma_f32_32x32x16_bf16 v[66:81], v[120:123], v[90:93], v[34:49]
	s_waitcnt lgkmcnt(11)
	v_mfma_f32_32x32x16_bf16 v[50:65], v[124:127], v[90:93], v[34:49]
	v_sub_f32_e32 v249, v160, v248
	v_cvt_pk_bf16_f32 v162, v249, 0
	v_lshlrev_b32_e32 v162, 16, v162
	s_waitcnt lgkmcnt(10)
	v_mfma_f32_32x32x16_bf16 v[66:81], v[128:131], v[82:85], v[66:81]
	s_waitcnt lgkmcnt(9)
	v_mfma_f32_32x32x16_bf16 v[50:65], v[132:135], v[82:85], v[50:65]
	v_sub_f32_e32 v249, v249, v162
	v_cvt_pk_bf16_f32 v163, v249, 0
	v_and_b32_e32 v157, 0xffff, v163
	v_lshlrev_b32_e32 v163, 16, v163
	s_waitcnt lgkmcnt(8)
	v_mfma_f32_32x32x16_bf16 v[66:81], v[136:139], v[86:89], v[66:81]
	s_waitcnt lgkmcnt(7)
	v_mfma_f32_32x32x16_bf16 v[50:65], v[170:173], v[86:89], v[50:65]
	v_sub_f32_e32 v249, v249, v163
	v_cvt_pk_bf16_f32 v249, v249, 0
	v_or_b32_e32 v162, 0x3f80, v162
	v_lshl_or_b32 v249, v249, 16, v157
	v_cndmask_b32_e64 v140, 0, v114, s[46:47]
	v_cndmask_b32_e64 v142, 0, v249, s[46:47]
	v_cndmask_b32_e64 v141, 0, v162, s[46:47]
	v_mov_b32_e32 v143, v1
	s_waitcnt lgkmcnt(6)
	v_mfma_f32_32x32x16_bf16 v[66:81], v[244:247], v[94:97], v[66:81]
	s_waitcnt lgkmcnt(5)
	v_mfma_f32_32x32x16_bf16 v[50:65], v[106:109], v[94:97], v[50:65]
	s_waitcnt lgkmcnt(4)
	v_mfma_f32_32x32x16_bf16 v[66:81], v[110:113], v[140:143], v[66:81]
	s_waitcnt lgkmcnt(3)
	v_mfma_f32_32x32x16_bf16 v[50:65], v[116:119], v[140:143], v[50:65]
	s_waitcnt lgkmcnt(0)
	s_barrier
	s_add_i32 s99, s99, 1
	s_add_i32 s94, s94, 1
	s_add_i32 s97, s97, 4
	s_add_i32 s98, s98, 64
	s_add_i32 s0, s95, 0
	s_cmp_le_i32 s99, s0
	s_cbranch_scc1 .Lfb_s_top
